# v34 + HGRN-in slab 1: 20 units pre-run by idle CUs during the 4-tile tail round of phase 5 (HGRN-out slab 0); phase 6 then needs 5 rounds instead of 6
# speedup vs baseline: 1.0142x; 1.0047x over previous
; #define PG8_STAGE(bufoff, gbase, voff) do { _Pragma("unroll") for (int _i = 0; _i < 2; ++_i) \
;         __builtin_amdgcn_global_load_lds((const unsigned*)((const char*)(gbase) + (voff)[_i]), (PG8_LAS unsigned*)(lds + (bufoff) + ldsw + _i * 8192), 16, 0, 0); } while (0)
;     __host__ __device__ bool next(int i, Unit& u) const {
;     ...
;         int wgid = (int)L; { const int q = nwg / NXCD, r = nwg % NXCD, xcd = wgid % NXCD, off = wgid / NXCD; wgid = (xcd < r ? xcd * (q + 1) : r * (q + 1) + (xcd - r) * q) + off; }
;         const int nig = WGM * nN, gid = wgid / nig, fm = gid * WGM, gsz = (nM - fm) < WGM ? (nM - fm) : WGM;
;         u.pm = fm + ((wgid % nig) % gsz); u.pn = (wgid % nig) / gsz; return true;
; template <class Epi, class Sched, bool ALIGN_EPI = false, bool SP2 = false>
; __device__ __forceinline__ void gemm_phase(PG8_LAS unsigned char* lds, const Gemm g, const Sched& S, const Epi& E, int tid_in) {
;     ...
;     for (int i = 0; i < 2; ++i) { int R, C; stage_rc(tid * 16 + i * 8192, R, C); const int Rb = Epi::PERM ? ((R & ~31) + perm32(R & 31)) : R;
;         voffA[i] = (unsigned)(R * g.lda + C) * 2u; voffB[i] = (unsigned)(Rb * K + C) * 2u; }
;     const size_t kstep = (size_t)(BK * 2);
;     const size_t hstep = (size_t)HALF * K * 2;
;     const size_t hstepA = (size_t)HALF * g.lda * 2;
;     const size_t tstepA = (size_t)g.a_tile_rows * g.lda * 2, tstepB = 2 * hstep;
;     const unsigned ldsw = (unsigned)wid * 1024u;
;     const int aoff = lds_byte(wr * 64 + fr, fq * 8), boff = lds_byte(wc * 32 + fr, fq * 8);
;     ...
;     Unit cur, nxt; int ui = 0;
;     if (!S.next(0, cur)) return;
;     f32x4 acc[2][2][4][2];
; #pragma unroll
;     for (int a = 0; a < 2; ++a)
; #pragma unroll
;         for (int b = 0; b < 2; ++b)
; #pragma unroll
;             for (int m = 0; m < 4; ++m)
; #pragma unroll
;                 for (int n = 0; n < 2; ++n) acc[a][b][m][n] = (f32x4){0.f, 0.f, 0.f, 0.f};
;     bf16x8 At[4][2], B0[2][2], B1[2][2];
;     const char* cA = (const char*)g.A + (size_t)cur.pm * tstepA + a_unit_off(g, cur.pn); const char* cB = (const char*)g.Bt + (size_t)cur.pn * tstepB;
;     S.a_ready(cur);
;     if constexpr (SP2) {
;         PG8_STAGE(PG8_SB(0, 0), cB, voffB); PG8_STAGE(PG8_SB(0, 1), cB + hstep, voffB); PG8_STAGE(PG8_SA(0, 0), cA, voffA); PG8_STAGE(PG8_SA(0, 1), cA + hstepA, voffA);
;         if (wr == 1) PG8_BAR;
.LBB0_691:
	s_andn2_b64 vcc, exec, s[0:1]
	s_cbranch_vccnz .LBB0_752
	v_readlane_b32 s0, v253, 6
	v_readlane_b32 s1, v253, 7
	s_movk_i32 s20, 0x400
	s_andn2_b64 vcc, exec, s[0:1]
	v_cndmask_b32_e64 v0, 0, 1, s[0:1]
	v_cmp_ne_u32_e64 s[36:37], 1, v0
	v_readfirstlane_b32 s12, v202
	s_cbranch_vccnz .LBB0_694
	v_readlane_b32 s2, v254, 15
	v_readlane_b32 s63, v254, 13
	s_movk_i32 s98, 0x514
	s_cmp_lg_u32 s94, 0x100
	s_cbranch_scc1 .Lpre1_done
	s_cmp_eq_u32 s99, 1
	s_cbranch_scc0 .Lpre1_real
	s_movk_i32 s98, 0x100
	s_branch .Lpre1_done
.Lpre1_real:
	s_cmp_eq_u32 s83, 6
	s_cbranch_scc0 .Lpre1_done
	s_movk_i32 s98, 0x500
	s_and_b32 s100, s96, 7
	s_cmp_lg_u32 s100, 0
	s_cbranch_scc1 .Lpre1_done
	s_lshr_b32 s101, s96, 3
	s_add_i32 s101, s101, -1
	s_cmp_gt_u32 s101, 19
	s_cbranch_scc1 .Lpre1_done
	s_and_b32 s100, s101, 7
	s_lshr_b32 s101, s101, 3
	s_addk_i32 s101, 0xa0
	s_mul_i32 s2, s100, 0xa2
	s_min_u32 s100, s100, 4
	s_add_i32 s2, s2, s100
	s_add_i32 s2, s2, s101
	s_mul_hi_u32 s63, s2, 0x66666667
	s_lshr_b32 s63, s63, 6
	s_mul_i32 s100, s63, 0xa0
	s_sub_i32 s100, s2, s100
	s_lshl_b32 s63, s63, 3
	s_cmp_eq_u32 s63, 0x40
	s_cbranch_scc1 .Lpre1_g8
	s_lshr_b32 s2, s100, 3
	s_and_b32 s100, s100, 7
	s_add_i32 s63, s63, s100
	s_branch .Lpre1_done
.Lpre1_g8:
	s_mov_b32 s2, s100
.Lpre1_done:
.LBB0_694:
	s_and_b64 vcc, exec, s[36:37]
	s_cbranch_vccnz .LBB0_752
	s_waitcnt lgkmcnt(0)
	v_bfe_i32 v3, v202, 27, 1
	v_lshlrev_b32_e32 v2, 4, v202
	v_lshrrev_b32_e32 v3, 22, v3
	v_add_u32_e32 v3, v2, v3
	v_and_b32_e32 v3, 0xfffffc00, v3
	v_sub_u32_e32 v3, v2, v3
	v_ashrrev_i32_e32 v0, 31, v202
	v_lshrrev_b32_e32 v4, 4, v3
	v_lshrrev_b32_e32 v0, 26, v0
	v_bitop3_b32 v3, v4, v3, 32 bitop3:0x6c
	v_add_u32_e32 v0, v202, v0
	v_ashrrev_i32_e32 v5, 31, v3
	v_readlane_b32 s0, v255, 7
	v_ashrrev_i32_e32 v0, 6, v0
	v_lshrrev_b32_e32 v5, 26, v5
	v_readlane_b32 s1, v255, 8
	v_lshlrev_b32_e32 v4, 3, v0
	v_add_u32_e32 v5, v3, v5
	s_ashr_i32 s1, s0, 31
	v_and_b32_e32 v4, -16, v4
	v_ashrrev_i32_e32 v6, 6, v5
	s_mov_b64 s[36:37], s[0:1]
	s_lshl_b64 s[0:1], s[0:1], 11
	v_add_u32_e32 v4, v6, v4
	v_and_b32_e32 v5, 0xc0, v5
	s_add_u32 s24, s4, s0
	v_sub_u32_e32 v3, v3, v5
	v_lshlrev_b32_e32 v5, 1, v4
	v_lshrrev_b32_e32 v7, 2, v4
	v_and_b32_e32 v6, 3, v6
	s_mov_b32 s0, 0x7fffffe0
	v_lshlrev_b32_e32 v0, 5, v0
	v_ashrrev_i16_sdwa v3, v197, sext(v3) dst_sel:DWORD dst_unused:UNUSED_PAD src0_sel:DWORD src1_sel:BYTE_0
	v_and_b32_e32 v5, 24, v5
	v_and_b32_e32 v7, 4, v7
	v_and_or_b32 v6, v4, s0, v6
	v_and_b32_e32 v0, 32, v0
	v_bfe_i32 v14, v3, 0, 16
	v_or3_b32 v5, v6, v7, v5
	v_add_u32_e32 v3, v0, v14
	v_mul_lo_u32 v15, s20, v4
	v_mul_lo_u32 v4, s20, v5
	v_add_u32_e32 v2, 0x2000, v2
	v_add_lshl_u32 v130, v15, v3, 1
	v_add_lshl_u32 v132, v4, v3, 1
	v_ashrrev_i32_e32 v3, 31, v2
	v_lshrrev_b32_e32 v3, 22, v3
	v_add_u32_e32 v3, v2, v3
	v_ashrrev_i32_e32 v3, 10, v3
	v_mul_i32_i24_e32 v4, 0x400, v3
	v_sub_u32_e32 v2, v2, v4
	v_lshrrev_b32_e32 v4, 4, v2
	v_bitop3_b32 v2, v4, v2, 32 bitop3:0x6c
	v_ashrrev_i32_e32 v5, 31, v2
	v_lshrrev_b32_e32 v5, 26, v5
	s_addc_u32 s48, s5, s1
	v_lshlrev_b32_e32 v4, 3, v3
	v_add_u32_e32 v5, v2, v5
	s_add_u32 s49, s4, 0x4100000
	v_and_b32_e32 v4, -16, v4
	v_ashrrev_i32_e32 v6, 6, v5
	s_addc_u32 s50, s5, 0
	v_add_u32_e32 v4, v6, v4
	v_and_b32_e32 v6, 3, v6
	s_ashr_i32 s21, s20, 31
	v_and_or_b32 v6, v4, s0, v6
	s_lshl_b64 s[10:11], s[20:21], 9
	s_ashr_i32 s0, s63, 31
	s_mul_i32 s0, s10, s0
	s_mul_hi_u32 s1, s10, s63
	s_add_i32 s18, s1, s0
	s_lshr_b64 s[0:1], s[20:21], 23
	s_mul_i32 s1, s0, s63
	s_add_i32 s18, s18, s1
	s_ashr_i32 s1, s2, 31
	s_mul_i32 s1, s10, s1
	s_mul_hi_u32 s22, s10, s2
	s_ashr_i32 s13, s12, 6
	v_lshlrev_b32_e32 v3, 5, v3
	s_add_i32 s1, s22, s1
	s_mul_i32 s0, s0, s2
	v_and_b32_e32 v16, 32, v3
	v_and_b32_e32 v3, 0xc0, v5
	s_ashr_i32 s15, s12, 8
	s_lshl_b64 s[8:9], s[20:21], 8
	s_lshl_b32 s51, s13, 10
	s_add_i32 s1, s1, s0
	s_mul_i32 s0, s10, s2
	v_sub_u32_e32 v2, v2, v3
	v_lshlrev_b32_e32 v3, 1, v4
	v_lshrrev_b32_e32 v5, 2, v4
	s_add_u32 s40, s49, s0
	v_ashrrev_i16_sdwa v2, v197, sext(v2) dst_sel:DWORD dst_unused:UNUSED_PAD src0_sel:DWORD src1_sel:BYTE_0
	v_and_b32_e32 v3, 24, v3
	v_and_b32_e32 v5, 4, v5
	s_addc_u32 s41, s50, s1
	s_add_i32 s52, s51, 0
	v_bfe_i32 v17, v2, 0, 16
	v_or3_b32 v3, v6, v5, v3
	s_add_i32 m0, s52, 0x10000
	v_add_u32_e32 v2, v16, v17
	v_mul_lo_u32 v3, s20, v3
	global_load_lds_dwordx4 v132, s[40:41]
	s_add_i32 m0, s52, 0x12000
	v_add_lshl_u32 v136, v3, v2, 1
	s_add_u32 s0, s40, s8
	global_load_lds_dwordx4 v136, s[40:41]
	s_addc_u32 s1, s41, s9
	s_add_i32 m0, s52, 0x14000
	s_mul_i32 s19, s10, s63
	global_load_lds_dwordx4 v132, s[0:1]
	s_add_i32 m0, s52, 0x16000
	s_add_u32 s46, s24, s19
	s_addc_u32 s47, s48, s18
	s_add_i32 s53, s52, 0x2000
	v_mul_lo_u32 v18, s20, v4
	global_load_lds_dwordx4 v136, s[0:1]
	s_mov_b32 m0, s52
	s_add_u32 s18, s46, s8
	v_add_lshl_u32 v134, v18, v2, 1
	global_load_lds_dwordx4 v130, s[46:47]
	s_mov_b32 m0, s53
	s_addc_u32 s19, s47, s9
	s_add_i32 s54, s52, 0x4000
	global_load_lds_dwordx4 v134, s[46:47]
	s_mov_b32 m0, s54
	s_add_i32 s55, s52, 0x6000
	global_load_lds_dwordx4 v130, s[18:19]
	s_mov_b32 m0, s55
	v_mov_b32_e32 v133, v1
	global_load_lds_dwordx4 v134, s[18:19]
	v_mov_b32_e32 v137, v1
	v_mov_b32_e32 v131, v1
	v_mov_b32_e32 v135, v1
	s_cmp_eq_u32 s15, 1
	v_lshl_add_u64 v[10:11], s[40:41], 0, v[132:133]
	v_lshl_add_u64 v[6:7], s[40:41], 0, v[136:137]
	v_lshl_add_u64 v[4:5], s[0:1], 0, v[132:133]
	v_lshl_add_u64 v[2:3], s[0:1], 0, v[136:137]
	v_lshl_add_u64 v[8:9], s[46:47], 0, v[130:131]
	s_cselect_b64 s[18:19], -1, 0
	s_cmp_lg_u32 s15, 1
	v_lshl_add_u64 v[12:13], s[46:47], 0, v[134:135]
	s_cbranch_scc1 .LBB0_697
	s_barrier

;     __host__ __device__ bool next(int i, Unit& u) const {
;         const long L = (long)i * G + c; if (L >= nwg) return false;
; template <class Epi, class Sched, bool ALIGN_EPI = false, bool SP2 = false>
; __device__ __forceinline__ void gemm_phase(PG8_LAS unsigned char* lds, const Gemm g, const Sched& S, const Epi& E, int tid_in) {
;     ...
;         const bool has_next = S.next(ui + 1, nxt);
.LBB0_700:
	s_add_i32 s60, s60, 1
	s_mul_i32 s12, s60, s87
	s_mul_hi_u32 s13, s60, s94
	s_add_i32 s13, s13, s12
	s_mul_i32 s12, s60, s94
	s_add_u32 s12, s12, s96
	s_addc_u32 s13, s13, s97
	v_mov_b32_e32 v2, s98
	v_mov_b32_e32 v3, 0
	v_cmp_lt_i64_e64 s[38:39], s[12:13], v[2:3]
	v_cmp_ge_i64_e32 vcc, s[12:13], v[2:3]
	s_cbranch_vccnz .LBB0_706
	s_ashr_i32 s13, s12, 31
	s_lshr_b32 s13, s13, 29
	s_add_i32 s15, s12, s13
	s_and_b32 s13, s15, -8
	s_sub_i32 s36, s12, s13
	s_cmp_gt_i32 s36, 3
	s_mov_b64 s[12:13], -1
	s_cbranch_scc0 .LBB0_703
	s_mul_i32 s12, s36, 0xa2
	s_add_i32 s37, s12, 4
	s_mov_b64 s[12:13], 0

; __global__ void __launch_bounds__(512, 2) fwd_mega(Args a_) {
;     ...
;         int kind = 15, slab = 0;
;         if (ph == 0) kind = 0;
;         else if (ph <= 10) { const int q = (ph - 1) % 5; slab = (ph - 1) / 5; kind = q == 0 ? 1 : (q == 1 ? 14 : (q == 2 ? 2 : (q == 3 ? 3 : 4))); }
;         else if (ph == 11) kind = 5; else if (ph == 12) kind = 6;
;         else if (ph <= 26) { kind = 7 + (ph - 13) % 7; slab = (ph - 13) / 7; }
;         else if (ph == 27) { kind = 5; slab = 1; } else if (ph == 28) { kind = 6; slab = 1; }
;     ...
;         default: if (PHM & 2048) final_norm((const bf16*)(ws + WS_HBNEW), (const float*)(ws + WS_PB), ap->in[5], ap->out, tid); break;
;         }
;         if (phc < 29) { unsigned z2 = 0u; asm volatile("" : "+v"(z2)); const int t2 = wave_s * 64 + (int)__builtin_amdgcn_mbcnt_hi(~0u, __builtin_amdgcn_mbcnt_lo(~0u, z2)); xcd_barrier(xbar, t2); }
.LBB0_961:
	s_cmp_eq_u32 s99, 1
	s_cbranch_scc1 .Lpre_back
	s_cmp_lg_u32 s94, 0x100
	s_cbranch_scc1 .Lpre_none
	s_cmp_eq_u32 s83, 5
	s_cbranch_scc1 .Lpre_chk1
	s_cmp_eq_u32 s83, 10
	s_cselect_b32 s100, 0, 1
	s_cbranch_scc1 .Lpre_chk
	s_cmp_eq_u32 s83, 26
	s_cbranch_scc0 .Lpre_none
.Lpre_chk:
	s_and_b32 s101, s96, 7
	s_cmp_gt_u32 s101, 2
	s_cbranch_scc1 .Lpre_none
	s_lshr_b32 s101, s96, 3
	s_add_i32 s101, s101, -1
	s_cmp_gt_u32 s101, 21
	s_cbranch_scc1 .Lpre_none
	s_mov_b32 s99, 1
	s_mov_b32 s65, 5
	s_mov_b32 s40, s100
.Lpre_go:
	s_branch .Ltramp_b50
.Lpre_chk1:
	s_and_b32 s101, s96, 7
	s_cmp_lg_u32 s101, 0
	s_cbranch_scc1 .Lpre_none
	s_lshr_b32 s101, s96, 3
	s_add_i32 s101, s101, -1
	s_cmp_gt_u32 s101, 19
	s_cbranch_scc1 .Lpre_none
	s_mov_b32 s99, 1
	s_mov_b32 s65, 1
	s_mov_b32 s40, 1
	s_branch .Lpre_go
